# SSD in-proj dt column tile: the three column waves beyond N run the K-loop without MFMA/LDS reads (same barriers and LDS-DMA)
# baseline (speedup 1.0000x reference)
.LBB0_1160:
	s_and_b32 s0, s31, 7
	s_nop 0
	v_lshl_add_u32 v0, s0, 8, v238
	v_ashrrev_i32_e32 v1, 31, v0
	v_lshlrev_b64 v[0:1], 11, v[0:1]
	s_and_b32 s0, s35, 0xffffff00
	v_lshl_add_u64 v[172:173], v[168:169], 0, v[0:1]
	v_add_u32_e32 v0, s0, v198
	s_and_b32 s0, s30, 7
	v_ashrrev_i32_e32 v1, 31, v0
	s_or_b32 s0, s0, s34
	v_lshlrev_b64 v[0:1], 11, v[0:1]
	s_lshl_b32 s0, s0, 8
	v_lshl_add_u64 v[174:175], v[170:171], 0, v[0:1]
	v_add_u32_e32 v0, s0, v198
	s_lshl_b32 s24, s30, 5
	v_ashrrev_i32_e32 v1, 31, v0
	s_and_b32 s1, s24, 0xffffff00
	v_lshlrev_b64 v[0:1], 11, v[0:1]
	v_add_u32_e32 v2, s1, v198
	s_waitcnt vmcnt(0) lgkmcnt(0)
	s_barrier
	v_ashrrev_i32_e32 v3, 31, v2
	v_lshl_add_u64 v[0:1], v[154:155], 0, v[0:1]
	v_readfirstlane_b32 s20, v203
	s_mov_b32 m0, s20
	s_nop 0
	global_load_lds_dwordx4 v[0:1], off
	s_mov_b64 s[26:27], 0x40000
	v_lshlrev_b64 v[2:3], 11, v[2:3]
	v_lshl_add_u64 v[4:5], v[0:1], 0, s[26:27]
	s_add_i32 s21, s20, 0x2000
	s_mov_b32 m0, s21
	s_nop 0
	global_load_lds_dwordx4 v[4:5], off
	v_lshl_add_u64 v[2:3], v[156:157], 0, v[2:3]
	s_add_i32 s21, s20, 0x4000
	s_mov_b32 m0, s21
	s_nop 0
	global_load_lds_dwordx4 v[2:3], off
	v_lshl_add_u64 v[4:5], v[2:3], 0, s[26:27]
	s_add_i32 s21, s20, 0x6000
	s_mov_b32 m0, s21
	s_nop 0
	global_load_lds_dwordx4 v[4:5], off
	s_add_i32 s21, s20, 0x8000
	v_lshl_add_u64 v[4:5], v[0:1], 0, 64
	s_mov_b32 m0, s21
	s_nop 0
	global_load_lds_dwordx4 v[4:5], off
	s_mov_b64 s[22:23], 0x40040
	v_lshl_add_u64 v[4:5], v[0:1], 0, s[22:23]
	s_add_i32 s21, s20, 0xa000
	s_mov_b32 m0, s21
	s_nop 0
	global_load_lds_dwordx4 v[4:5], off
	v_lshl_add_u64 v[4:5], v[2:3], 0, 64
	s_add_i32 s21, s20, 0xc000
	s_mov_b32 m0, s21
	s_nop 0
	global_load_lds_dwordx4 v[4:5], off
	v_lshl_add_u64 v[4:5], v[2:3], 0, s[22:23]
	s_add_i32 s21, s20, 0xe000
	s_mov_b32 m0, s21
	s_nop 0
	global_load_lds_dwordx4 v[4:5], off
	s_mov_b64 s[22:23], 0x80
	s_add_i32 s21, s20, 0x10000
	v_lshl_add_u64 v[4:5], v[0:1], 0, s[22:23]
	s_mov_b32 m0, s21
	s_nop 0
	global_load_lds_dwordx4 v[4:5], off
	s_mov_b64 s[28:29], 0x40080
	v_lshl_add_u64 v[0:1], v[0:1], 0, s[28:29]
	s_add_i32 s21, s20, 0x12000
	s_mov_b32 m0, s21
	s_nop 0
	global_load_lds_dwordx4 v[0:1], off
	v_lshl_add_u64 v[0:1], v[2:3], 0, s[22:23]
	s_add_i32 s21, s20, 0x14000
	s_mov_b32 m0, s21
	s_nop 0
	global_load_lds_dwordx4 v[0:1], off
	v_lshl_add_u64 v[0:1], v[2:3], 0, s[28:29]
	s_add_i32 s20, s20, 0x16000
	s_mov_b32 m0, s20
	s_nop 0
	global_load_lds_dwordx4 v[0:1], off
	v_mov_b32_e32 v130, 0
	v_mov_b32_e32 v134, 0
	v_mov_b32_e32 v0, 0
	s_mov_b32 s20, 0x18000
	v_mov_b32_e32 v1, v0
	v_mov_b32_e32 v2, v0
	v_mov_b32_e32 v3, v0
	v_mov_b32_e32 v4, v0
	v_mov_b32_e32 v5, v0
	v_mov_b32_e32 v6, v0
	v_mov_b32_e32 v7, v0
	v_mov_b32_e32 v8, v0
	v_mov_b32_e32 v9, v0
	v_mov_b32_e32 v10, v0
	v_mov_b32_e32 v11, v0
	v_mov_b32_e32 v12, v0
	v_mov_b32_e32 v13, v0
	v_mov_b32_e32 v14, v0
	v_mov_b32_e32 v15, v0
	v_mov_b32_e32 v16, v0
	v_mov_b32_e32 v17, v0
	v_mov_b32_e32 v18, v0
	v_mov_b32_e32 v19, v0
	v_mov_b32_e32 v20, v0
	v_mov_b32_e32 v21, v0
	v_mov_b32_e32 v22, v0
	v_mov_b32_e32 v23, v0
	v_mov_b32_e32 v24, v0
	v_mov_b32_e32 v25, v0
	v_mov_b32_e32 v26, v0
	v_mov_b32_e32 v27, v0
	v_mov_b32_e32 v28, v0
	v_mov_b32_e32 v29, v0
	v_mov_b32_e32 v30, v0
	v_mov_b32_e32 v31, v0
	v_mov_b32_e32 v32, v0
	v_mov_b32_e32 v33, v0
	v_mov_b32_e32 v34, v0
	v_mov_b32_e32 v35, v0
	v_mov_b32_e32 v36, v0
	v_mov_b32_e32 v37, v0
	v_mov_b32_e32 v38, v0
	v_mov_b32_e32 v39, v0
	v_mov_b32_e32 v40, v0
	v_mov_b32_e32 v41, v0
	v_mov_b32_e32 v42, v0
	v_mov_b32_e32 v43, v0
	v_mov_b32_e32 v44, v0
	v_mov_b32_e32 v45, v0
	v_mov_b32_e32 v46, v0
	v_mov_b32_e32 v47, v0
	v_mov_b32_e32 v48, v0
	v_mov_b32_e32 v49, v0
	v_mov_b32_e32 v50, v0
	v_mov_b32_e32 v51, v0
	v_mov_b32_e32 v52, v0
	v_mov_b32_e32 v53, v0
	v_mov_b32_e32 v54, v0
	v_mov_b32_e32 v55, v0
	v_mov_b32_e32 v56, v0
	v_mov_b32_e32 v57, v0
	v_mov_b32_e32 v58, v0
	v_mov_b32_e32 v59, v0
	v_mov_b32_e32 v60, v0
	v_mov_b32_e32 v61, v0
	v_mov_b32_e32 v62, v0
	v_mov_b32_e32 v63, v0
	v_mov_b32_e32 v64, v0
	v_mov_b32_e32 v65, v0
	v_mov_b32_e32 v66, v0
	v_mov_b32_e32 v67, v0
	v_mov_b32_e32 v68, v0
	v_mov_b32_e32 v69, v0
	v_mov_b32_e32 v70, v0
	v_mov_b32_e32 v71, v0
	v_mov_b32_e32 v72, v0
	v_mov_b32_e32 v73, v0
	v_mov_b32_e32 v74, v0
	v_mov_b32_e32 v75, v0
	v_mov_b32_e32 v76, v0
	v_mov_b32_e32 v77, v0
	v_mov_b32_e32 v78, v0
	v_mov_b32_e32 v79, v0
	v_mov_b32_e32 v80, v0
	v_mov_b32_e32 v81, v0
	v_mov_b32_e32 v82, v0
	v_mov_b32_e32 v83, v0
	v_mov_b32_e32 v84, v0
	v_mov_b32_e32 v85, v0
	v_mov_b32_e32 v86, v0
	v_mov_b32_e32 v87, v0
	v_mov_b32_e32 v88, v0
	v_mov_b32_e32 v89, v0
	v_mov_b32_e32 v90, v0
	v_mov_b32_e32 v91, v0
	v_mov_b32_e32 v92, v0
	v_mov_b32_e32 v93, v0
	v_mov_b32_e32 v94, v0
	v_mov_b32_e32 v95, v0
	v_mov_b32_e32 v96, v0
	v_mov_b32_e32 v97, v0
	v_mov_b32_e32 v98, v0
	v_mov_b32_e32 v99, v0
	v_mov_b32_e32 v100, v0
	v_mov_b32_e32 v101, v0
	v_mov_b32_e32 v102, v0
	v_mov_b32_e32 v103, v0
	v_mov_b32_e32 v104, v0
	v_mov_b32_e32 v105, v0
	v_mov_b32_e32 v106, v0
	v_mov_b32_e32 v107, v0
	v_mov_b32_e32 v108, v0
	v_mov_b32_e32 v109, v0
	v_mov_b32_e32 v110, v0
	v_mov_b32_e32 v111, v0
	v_mov_b32_e32 v112, v0
	v_mov_b32_e32 v113, v0
	v_mov_b32_e32 v114, v0
	v_mov_b32_e32 v115, v0
	v_mov_b32_e32 v116, v0
	v_mov_b32_e32 v117, v0
	v_mov_b32_e32 v118, v0
	v_mov_b32_e32 v119, v0
	v_mov_b32_e32 v120, v0
	v_mov_b32_e32 v121, v0
	v_mov_b32_e32 v122, v0
	v_mov_b32_e32 v123, v0
	v_mov_b32_e32 v124, v0
	v_mov_b32_e32 v125, v0
	v_mov_b32_e32 v126, v0
	v_mov_b32_e32 v127, v0
	v_mov_b32_e32 v135, v134
	v_mov_b32_e32 v136, v134
	v_mov_b32_e32 v137, v134
	v_mov_b32_e32 v138, v134
	v_mov_b32_e32 v139, v134
	v_mov_b32_e32 v140, v134
	v_mov_b32_e32 v141, v134
	v_mov_b32_e32 v146, v134
	v_mov_b32_e32 v147, v134
	v_mov_b32_e32 v148, v134
	v_mov_b32_e32 v149, v134
	v_mov_b32_e32 v150, v134
	v_mov_b32_e32 v151, v134
	v_mov_b32_e32 v152, v134
	v_mov_b32_e32 v153, v134
	v_mov_b32_e32 v131, v130
	v_mov_b32_e32 v132, v130
	v_mov_b32_e32 v133, v130
	v_mov_b32_e32 v142, v130
	v_mov_b32_e32 v143, v130
	v_mov_b32_e32 v144, v130
	v_mov_b32_e32 v145, v130
	v_readfirstlane_b32 s21, v196
	s_or_b32 s21, s21, s1
	s_cmpk_ge_i32 s21, 0x1840
	s_cbranch_scc1 .Lnm_1161
.LBB0_1161:
	s_and_b32 s21, s20, 0x18000
	v_add_u32_e32 v128, s21, v203
	s_add_i32 s21, s20, 0xfffe8000
	s_and_b32 s21, s21, 0x18000
	v_or_b32_e32 v222, s21, v202
	v_add_u32_e32 v223, s21, v199
	s_waitcnt lgkmcnt(0)
	v_mfma_f32_32x32x16_bf16 v[112:127], v[150:153], v[142:145], v[112:127]
	v_mfma_f32_32x32x16_bf16 v[96:111], v[150:153], v[130:133], v[96:111]
	s_waitcnt vmcnt(8)
	s_barrier
	v_add_u32_e32 v180, v222, v200
	v_add_u32_e32 v224, v223, v200
	ds_read_b128 v[176:179], v180 offset:16384
	ds_read_b128 v[180:183], v180 offset:18432
	ds_read_b128 v[184:187], v224
	v_mfma_f32_32x32x16_bf16 v[80:95], v[146:149], v[142:145], v[80:95]
	v_mfma_f32_32x32x16_bf16 v[64:79], v[146:149], v[130:133], v[64:79]
	ds_read_b128 v[188:191], v224 offset:2048
	v_readfirstlane_b32 s21, v128
	s_mov_b32 m0, s21
	s_nop 0
	global_load_lds_dwordx4 v[172:173], off
	v_mfma_f32_32x32x16_bf16 v[48:63], v[138:141], v[142:145], v[48:63]
	v_mfma_f32_32x32x16_bf16 v[32:47], v[138:141], v[130:133], v[32:47]
	ds_read_b128 v[192:195], v224 offset:4096
	s_add_i32 s22, s21, 0x2000
	v_lshl_add_u64 v[150:151], v[172:173], 0, s[26:27]
	s_mov_b32 m0, s22
	s_nop 0
	global_load_lds_dwordx4 v[150:151], off
	v_mfma_f32_32x32x16_bf16 v[16:31], v[134:137], v[142:145], v[16:31]
	v_mfma_f32_32x32x16_bf16 v[0:15], v[134:137], v[130:133], v[0:15]
	ds_read_b128 v[240:243], v224 offset:6144
	s_waitcnt lgkmcnt(3)
	v_mfma_f32_32x32x16_bf16 v[112:127], v[184:187], v[176:179], v[112:127]
	v_add_u32_e32 v128, v222, v201
	ds_read_b128 v[142:145], v128 offset:16384
	v_mfma_f32_32x32x16_bf16 v[96:111], v[184:187], v[180:183], v[96:111]
	ds_read_b128 v[130:133], v128 offset:18432
	s_add_i32 s22, s21, 0x6000
	s_addk_i32 s21, 0x4000
	s_mov_b32 m0, s21
	s_nop 0
	global_load_lds_dwordx4 v[174:175], off
	s_waitcnt lgkmcnt(4)
	v_mfma_f32_32x32x16_bf16 v[80:95], v[188:191], v[176:179], v[80:95]
	v_add_u32_e32 v128, v223, v201
	ds_read_b128 v[150:153], v128
	v_mfma_f32_32x32x16_bf16 v[64:79], v[188:191], v[180:183], v[64:79]
	ds_read_b128 v[146:149], v128 offset:2048
	s_waitcnt lgkmcnt(5)
	v_mfma_f32_32x32x16_bf16 v[48:63], v[192:195], v[176:179], v[48:63]
	ds_read_b128 v[138:141], v128 offset:4096
	v_mfma_f32_32x32x16_bf16 v[32:47], v[192:195], v[180:183], v[32:47]
	ds_read_b128 v[134:137], v128 offset:6144
	v_lshl_add_u64 v[224:225], v[174:175], 0, s[26:27]
	s_mov_b32 m0, s22
	s_nop 0
	global_load_lds_dwordx4 v[224:225], off
	s_waitcnt lgkmcnt(6)
	v_mfma_f32_32x32x16_bf16 v[16:31], v[240:243], v[176:179], v[16:31]
	s_add_i32 s20, s20, 0x8000
	v_lshl_add_u64 v[172:173], v[172:173], 0, 64
	v_lshl_add_u64 v[174:175], v[174:175], 0, 64
	s_cmp_eq_u32 s20, 0x100000
	v_mfma_f32_32x32x16_bf16 v[0:15], v[240:243], v[180:183], v[0:15]
	s_cbranch_scc0 .LBB0_1161
	s_branch .Lnm_done_1161
.Lnm_1161:
	s_and_b32 s21, s20, 0x18000
	v_add_u32_e32 v128, s21, v203
	s_add_i32 s21, s20, 0xfffe8000
	s_and_b32 s21, s21, 0x18000
	v_or_b32_e32 v222, s21, v202
	v_add_u32_e32 v223, s21, v199
	s_waitcnt vmcnt(8)
	s_barrier
	v_add_u32_e32 v180, v222, v200
	v_add_u32_e32 v224, v223, v200
	v_readfirstlane_b32 s21, v128
	s_mov_b32 m0, s21
	s_nop 0
	global_load_lds_dwordx4 v[172:173], off
	s_add_i32 s22, s21, 0x2000
	v_lshl_add_u64 v[150:151], v[172:173], 0, s[26:27]
	s_mov_b32 m0, s22
	s_nop 0
	global_load_lds_dwordx4 v[150:151], off
	v_add_u32_e32 v128, v222, v201
	s_add_i32 s22, s21, 0x6000
	s_addk_i32 s21, 0x4000
	s_mov_b32 m0, s21
	s_nop 0
	global_load_lds_dwordx4 v[174:175], off
	v_add_u32_e32 v128, v223, v201
	v_lshl_add_u64 v[224:225], v[174:175], 0, s[26:27]
	s_mov_b32 m0, s22
	s_nop 0
	global_load_lds_dwordx4 v[224:225], off
	s_add_i32 s20, s20, 0x8000
	v_lshl_add_u64 v[172:173], v[172:173], 0, 64
	v_lshl_add_u64 v[174:175], v[174:175], 0, 64
	s_cmp_eq_u32 s20, 0x100000
	s_cbranch_scc0 .Lnm_1161
